# r11 + latent pass rewritten: gains hoisted out of the row loop, rows and rotary table values prefetched through a 4-deep register ring
# baseline (speedup 1.0000x reference)
.LBB0_160:
	s_cmp_gt_i32 s34, 2
	s_cselect_b64 s[0:1], -1, 0
	s_cmp_lt_i32 s35, 3
	s_cselect_b64 s[2:3], -1, 0
	s_or_b64 s[0:1], s[0:1], s[2:3]
	s_and_b64 vcc, exec, s[0:1]
	s_cbranch_vccnz .LBB0_220
	s_waitcnt vmcnt(0)
	v_mbcnt_lo_u32_b32 v14, -1, 0
	v_mbcnt_hi_u32_b32 v14, -1, v14
	s_mov_b32 s0, 0xc000
	v_add_u32_e32 v16, s84, v14
	v_ashrrev_i32_e32 v18, 6, v16
	v_lshl_add_u32 v0, s12, 3, v18
	v_cmp_gt_i32_e32 vcc, s0, v0
	v_and_b32_e32 v15, 63, v14
	v_lshlrev_b32_e32 v17, 3, v14
	s_and_saveexec_b64 s[52:53], vcc
	s_cbranch_execz .LBB0_174
	v_mbcnt_lo_u32_b32 v1, -1, 0
	v_mbcnt_hi_u32_b32 v1, -1, v1
	v_and_b32_e32 v6, 64, v1
	v_add_u32_e32 v6, 64, v6
	v_xor_b32_e32 v7, 32, v1
	v_cmp_lt_i32_e32 vcc, v7, v6
	v_lshlrev_b32_e32 v10, 4, v15
	v_mov_b32_e32 v11, 0
	v_cndmask_b32_e32 v7, v1, v7, vcc
	v_lshlrev_b32_e32 v19, 2, v7
	v_xor_b32_e32 v7, 16, v1
	v_cmp_lt_i32_e32 vcc, v7, v6
	s_add_u32 s54, s70, 0x16a0000
	v_lshl_add_u64 v[2:3], s[70:71], 0, v[10:11]
	v_cndmask_b32_e32 v7, v1, v7, vcc
	v_lshlrev_b32_e32 v20, 2, v7
	v_xor_b32_e32 v7, 8, v1
	v_cmp_lt_i32_e32 vcc, v7, v6
	s_addc_u32 s55, s71, 0
	s_mov_b64 s[16:17], 0x1dfa0000
	v_cndmask_b32_e32 v7, v1, v7, vcc
	v_lshlrev_b32_e32 v21, 2, v7
	v_xor_b32_e32 v7, 4, v1
	v_cmp_lt_i32_e32 vcc, v7, v6
	s_add_u32 s56, s70, 0x1720000
	s_mov_b64 s[0:1], 0x107a0000
	v_cndmask_b32_e32 v7, v1, v7, vcc
	v_lshlrev_b32_e32 v22, 2, v7
	v_xor_b32_e32 v7, 2, v1
	v_cmp_lt_i32_e32 vcc, v7, v6
	s_addc_u32 s57, s71, 0
	v_lshl_add_u64 v[4:5], v[2:3], 0, s[0:1]
	v_cndmask_b32_e32 v7, v1, v7, vcc
	v_lshlrev_b32_e32 v23, 2, v7
	v_xor_b32_e32 v7, 1, v1
	v_cmp_lt_i32_e32 vcc, v7, v6
	v_mov_b32_e32 v6, 0xffffff00
	v_lshl_add_u32 v10, v15, 3, v6
	v_cndmask_b32_e32 v1, v1, v7, vcc
	v_lshlrev_b32_e32 v24, 2, v1
	v_and_b32_e32 v1, 48, v14
	v_lshl_add_u64 v[8:9], v[10:11], 1, s[70:71]
	v_cmp_eq_u32_e64 s[6:7], 32, v1
	v_and_b32_e32 v1, 8, v17
	v_lshl_add_u64 v[6:7], v[10:11], 2, s[48:49]
	v_lshl_add_u64 v[8:9], v[8:9], 0, s[16:17]
	v_lshlrev_b32_e32 v10, 5, v15
	s_mov_b64 s[16:17], 0x1c7a0000
	v_cmp_gt_u32_e64 s[0:1], 32, v15
	v_cmp_lt_u32_e64 s[2:3], 31, v15
	v_cmp_lt_u32_e64 s[4:5], 47, v15
	v_cmp_gt_u32_e64 s[8:9], 52, v15
	v_cmp_gt_u32_e64 s[10:11], 50, v15
	v_lshl_add_u64 v[10:11], s[44:45], 0, v[10:11]
	v_lshl_add_u64 v[12:13], v[2:3], 0, s[16:17]
	s_waitcnt lgkmcnt(0)
	s_lshl_b32 s16, s13, 3
	s_mov_b64 s[58:59], 0
	s_mov_b32 s17, 0x8000
	v_lshlrev_b32_e32 v25, 2, v1
	v_mov_b32_e32 v26, 0x358637bd
	s_mov_b32 s18, 0x800000
	s_mov_b32 s19, 0xbfff
	v_mov_b32_e32 v27, 0x7ff
	v_mov_b32_e32 v28, 0x1fff
	s_mov_b64 s[20:21], exec
	s_and_b64 exec, s[20:21], s[0:1]
	global_load_dwordx4 v[70:73], v[10:11], off
	global_load_dwordx4 v[74:77], v[10:11], off offset:16
	s_and_b64 exec, s[20:21], s[6:7]
	global_load_dwordx4 v[70:73], v[6:7], off
	global_load_dwordx4 v[74:77], v[6:7], off offset:16
	s_mov_b64 exec, s[20:21]
	s_mov_b32 s30, 0
	s_lshl_b32 s31, s16, 2
	v_mov_b32_e32 v97, v0
	v_min_i32_e32 v98, s19, v97
	v_cmp_gt_i32_e32 vcc, s17, v98
	v_ashrrev_i32_e32 v99, 31, v98
	v_lshlrev_b64 v[68:69], 10, v[98:99]
	v_lshl_add_u64 v[68:69], v[4:5], 0, v[68:69]
	v_cndmask_b32_e32 v96, v27, v28, vcc
	v_and_b32_e32 v96, v96, v98
	v_lshl_or_b32 v96, v96, 6, v25
	global_load_dwordx4 v[120:123], v96, s[56:57]
	global_load_dwordx4 v[124:127], v96, s[56:57] offset:16
	global_load_dwordx4 v[128:131], v96, s[54:55]
	global_load_dwordx4 v[132:135], v96, s[54:55] offset:16
	global_load_dwordx4 v[100:103], v[68:69], off
	v_add_u32_e32 v97, s16, v97
	v_min_i32_e32 v98, s19, v97
	v_cmp_gt_i32_e32 vcc, s17, v98
	v_ashrrev_i32_e32 v99, 31, v98
	v_lshlrev_b64 v[68:69], 10, v[98:99]
	v_lshl_add_u64 v[68:69], v[4:5], 0, v[68:69]
	v_cndmask_b32_e32 v96, v27, v28, vcc
	v_and_b32_e32 v96, v96, v98
	v_lshl_or_b32 v96, v96, 6, v25
	global_load_dwordx4 v[136:139], v96, s[56:57]
	global_load_dwordx4 v[140:143], v96, s[56:57] offset:16
	global_load_dwordx4 v[144:147], v96, s[54:55]
	global_load_dwordx4 v[148:151], v96, s[54:55] offset:16
	global_load_dwordx4 v[104:107], v[68:69], off
	v_add_u32_e32 v97, s16, v97
	v_min_i32_e32 v98, s19, v97
	v_cmp_gt_i32_e32 vcc, s17, v98
	v_ashrrev_i32_e32 v99, 31, v98
	v_lshlrev_b64 v[68:69], 10, v[98:99]
	v_lshl_add_u64 v[68:69], v[4:5], 0, v[68:69]
	v_cndmask_b32_e32 v96, v27, v28, vcc
	v_and_b32_e32 v96, v96, v98
	v_lshl_or_b32 v96, v96, 6, v25
	global_load_dwordx4 v[152:155], v96, s[56:57]
	global_load_dwordx4 v[156:159], v96, s[56:57] offset:16
	global_load_dwordx4 v[160:163], v96, s[54:55]
	global_load_dwordx4 v[164:167], v96, s[54:55] offset:16
	global_load_dwordx4 v[108:111], v[68:69], off
	v_add_u32_e32 v97, s16, v97
	v_min_i32_e32 v98, s19, v97
	v_cmp_gt_i32_e32 vcc, s17, v98
	v_ashrrev_i32_e32 v99, 31, v98
	v_lshlrev_b64 v[68:69], 10, v[98:99]
	v_lshl_add_u64 v[68:69], v[4:5], 0, v[68:69]
	v_cndmask_b32_e32 v96, v27, v28, vcc
	v_and_b32_e32 v96, v96, v98
	v_lshl_or_b32 v96, v96, 6, v25
	global_load_dwordx4 v[168:171], v96, s[56:57]
	global_load_dwordx4 v[172:175], v96, s[56:57] offset:16
	global_load_dwordx4 v[176:179], v96, s[54:55]
	global_load_dwordx4 v[180:183], v96, s[54:55] offset:16
	global_load_dwordx4 v[112:115], v[68:69], off
	v_add_u32_e32 v97, s16, v97
	s_branch .LBB0_164

.LBB0_164:
	v_ashrrev_i32_e32 v1, 31, v0
	v_add_u32_e32 v98, s31, v0
	v_min_i32_e32 v98, s19, v98
	v_cmp_gt_i32_e32 vcc, s17, v98
	v_ashrrev_i32_e32 v99, 31, v98
	v_lshlrev_b64 v[68:69], 10, v[98:99]
	v_lshl_add_u64 v[68:69], v[4:5], 0, v[68:69]
	v_cndmask_b32_e32 v96, v27, v28, vcc
	v_and_b32_e32 v96, v96, v98
	v_lshl_or_b32 v96, v96, 6, v25
	s_and_b32 s32, s30, 3
	s_add_i32 s30, s30, 1
	s_waitcnt vmcnt(15)
	s_cmp_eq_u32 s32, 0
	s_cbranch_scc1 .Llat164_s0
	s_cmp_eq_u32 s32, 1
	s_cbranch_scc1 .Llat164_s1
	s_cmp_eq_u32 s32, 2
	s_cbranch_scc1 .Llat164_s2
	v_mov_b32_e32 v34, v112
	v_mov_b32_e32 v35, v113
	v_mov_b32_e32 v36, v114
	v_mov_b32_e32 v37, v115
	v_mov_b32_e32 v80, v168
	v_mov_b32_e32 v81, v169
	v_mov_b32_e32 v82, v170
	v_mov_b32_e32 v83, v171
	v_mov_b32_e32 v84, v172
	v_mov_b32_e32 v85, v173
	v_mov_b32_e32 v86, v174
	v_mov_b32_e32 v87, v175
	v_mov_b32_e32 v88, v176
	v_mov_b32_e32 v89, v177
	v_mov_b32_e32 v90, v178
	v_mov_b32_e32 v91, v179
	v_mov_b32_e32 v92, v180
	v_mov_b32_e32 v93, v181
	v_mov_b32_e32 v94, v182
	v_mov_b32_e32 v95, v183
	global_load_dwordx4 v[168:171], v96, s[56:57]
	global_load_dwordx4 v[172:175], v96, s[56:57] offset:16
	global_load_dwordx4 v[176:179], v96, s[54:55]
	global_load_dwordx4 v[180:183], v96, s[54:55] offset:16
	global_load_dwordx4 v[112:115], v[68:69], off
	s_branch .Llat164_body
.Llat164_s0:
	v_mov_b32_e32 v34, v100
	v_mov_b32_e32 v35, v101
	v_mov_b32_e32 v36, v102
	v_mov_b32_e32 v37, v103
	v_mov_b32_e32 v80, v120
	v_mov_b32_e32 v81, v121
	v_mov_b32_e32 v82, v122
	v_mov_b32_e32 v83, v123
	v_mov_b32_e32 v84, v124
	v_mov_b32_e32 v85, v125
	v_mov_b32_e32 v86, v126
	v_mov_b32_e32 v87, v127
	v_mov_b32_e32 v88, v128
	v_mov_b32_e32 v89, v129
	v_mov_b32_e32 v90, v130
	v_mov_b32_e32 v91, v131
	v_mov_b32_e32 v92, v132
	v_mov_b32_e32 v93, v133
	v_mov_b32_e32 v94, v134
	v_mov_b32_e32 v95, v135
	global_load_dwordx4 v[120:123], v96, s[56:57]
	global_load_dwordx4 v[124:127], v96, s[56:57] offset:16
	global_load_dwordx4 v[128:131], v96, s[54:55]
	global_load_dwordx4 v[132:135], v96, s[54:55] offset:16
	global_load_dwordx4 v[100:103], v[68:69], off
	s_branch .Llat164_body
.Llat164_s1:
	v_mov_b32_e32 v34, v104
	v_mov_b32_e32 v35, v105
	v_mov_b32_e32 v36, v106
	v_mov_b32_e32 v37, v107
	v_mov_b32_e32 v80, v136
	v_mov_b32_e32 v81, v137
	v_mov_b32_e32 v82, v138
	v_mov_b32_e32 v83, v139
	v_mov_b32_e32 v84, v140
	v_mov_b32_e32 v85, v141
	v_mov_b32_e32 v86, v142
	v_mov_b32_e32 v87, v143
	v_mov_b32_e32 v88, v144
	v_mov_b32_e32 v89, v145
	v_mov_b32_e32 v90, v146
	v_mov_b32_e32 v91, v147
	v_mov_b32_e32 v92, v148
	v_mov_b32_e32 v93, v149
	v_mov_b32_e32 v94, v150
	v_mov_b32_e32 v95, v151
	global_load_dwordx4 v[136:139], v96, s[56:57]
	global_load_dwordx4 v[140:143], v96, s[56:57] offset:16
	global_load_dwordx4 v[144:147], v96, s[54:55]
	global_load_dwordx4 v[148:151], v96, s[54:55] offset:16
	global_load_dwordx4 v[104:107], v[68:69], off
	s_branch .Llat164_body
.Llat164_s2:
	v_mov_b32_e32 v34, v108
	v_mov_b32_e32 v35, v109
	v_mov_b32_e32 v36, v110
	v_mov_b32_e32 v37, v111
	v_mov_b32_e32 v80, v152
	v_mov_b32_e32 v81, v153
	v_mov_b32_e32 v82, v154
	v_mov_b32_e32 v83, v155
	v_mov_b32_e32 v84, v156
	v_mov_b32_e32 v85, v157
	v_mov_b32_e32 v86, v158
	v_mov_b32_e32 v87, v159
	v_mov_b32_e32 v88, v160
	v_mov_b32_e32 v89, v161
	v_mov_b32_e32 v90, v162
	v_mov_b32_e32 v91, v163
	v_mov_b32_e32 v92, v164
	v_mov_b32_e32 v93, v165
	v_mov_b32_e32 v94, v166
	v_mov_b32_e32 v95, v167
	global_load_dwordx4 v[152:155], v96, s[56:57]
	global_load_dwordx4 v[156:159], v96, s[56:57] offset:16
	global_load_dwordx4 v[160:163], v96, s[54:55]
	global_load_dwordx4 v[164:167], v96, s[54:55] offset:16
	global_load_dwordx4 v[108:111], v[68:69], off
.Llat164_body:
	v_and_b32_e32 v30, 0xffff0000, v34
	v_lshlrev_b32_e32 v29, 16, v34
	v_lshlrev_b32_e32 v31, 16, v35
	v_and_b32_e32 v32, 0xffff0000, v35
	v_lshlrev_b32_e32 v33, 16, v36
	v_and_b32_e32 v34, 0xffff0000, v36
	v_lshlrev_b32_e32 v35, 16, v37
	v_and_b32_e32 v36, 0xffff0000, v37
	v_mul_f32_e32 v37, v30, v30
	v_fmac_f32_e32 v37, v29, v29
	v_fmac_f32_e32 v37, v31, v31
	v_fmac_f32_e32 v37, v32, v32
	v_fmac_f32_e32 v37, v33, v33
	v_fmac_f32_e32 v37, v34, v34
	v_fmac_f32_e32 v37, v35, v35
	v_fmac_f32_e32 v37, v36, v36
	v_cndmask_b32_e64 v38, 0, v37, s[0:1]
	v_cndmask_b32_e64 v37, 0, v37, s[6:7]
	ds_bpermute_b32 v39, v19, v38
	ds_bpermute_b32 v40, v19, v37
	s_waitcnt lgkmcnt(1)
	v_add_f32_e32 v38, v38, v39
	s_waitcnt lgkmcnt(0)
	v_add_f32_e32 v37, v37, v40
	ds_bpermute_b32 v39, v20, v38
	ds_bpermute_b32 v40, v20, v37
	s_waitcnt lgkmcnt(1)
	v_add_f32_e32 v38, v38, v39
	s_waitcnt lgkmcnt(0)
	v_add_f32_e32 v39, v37, v40
	ds_bpermute_b32 v40, v21, v38
	ds_bpermute_b32 v41, v21, v39
	ds_bpermute_b32 v37, v23, v29
	s_waitcnt lgkmcnt(2)
	v_add_f32_e32 v42, v38, v40
	s_waitcnt lgkmcnt(1)
	v_add_f32_e32 v41, v39, v41
	ds_bpermute_b32 v43, v22, v42
	ds_bpermute_b32 v44, v22, v41
	ds_bpermute_b32 v38, v23, v30
	ds_bpermute_b32 v39, v23, v31
	ds_bpermute_b32 v40, v23, v32
	s_waitcnt lgkmcnt(4)
	v_add_f32_e32 v45, v42, v43
	s_waitcnt lgkmcnt(3)
	v_add_f32_e32 v44, v41, v44
	ds_bpermute_b32 v46, v23, v45
	ds_bpermute_b32 v48, v23, v44
	ds_bpermute_b32 v41, v23, v33
	ds_bpermute_b32 v42, v23, v34
	ds_bpermute_b32 v43, v23, v35
	s_waitcnt lgkmcnt(4)
	v_add_f32_e32 v47, v45, v46
	s_waitcnt lgkmcnt(3)
	v_add_f32_e32 v45, v44, v48
	ds_bpermute_b32 v48, v24, v47
	ds_bpermute_b32 v46, v24, v45
	ds_bpermute_b32 v44, v23, v36
	s_and_saveexec_b64 s[20:21], s[2:3]
	s_xor_b64 s[60:61], exec, s[20:21]
	s_cbranch_execz .LBB0_172
	s_and_saveexec_b64 s[20:21], s[4:5]
	s_xor_b64 s[62:63], exec, s[20:21]
	s_cbranch_execz .LBB0_169
	s_and_saveexec_b64 s[64:65], s[8:9]
	s_cbranch_execz .LBB0_168
	v_lshlrev_b64 v[62:63], 6, v[0:1]
	v_lshl_add_u64 v[62:63], v[2:3], 0, v[62:63]
	s_waitcnt lgkmcnt(1)
	v_add_co_u32_e32 v62, vcc, 0x1eb9f000, v62
	v_mul_f32_e32 v37, v80, v37
	v_mul_f32_e32 v38, v81, v38
	v_mul_f32_e32 v39, v82, v39
	v_mul_f32_e32 v40, v83, v40
	v_mul_f32_e32 v41, v84, v41
	v_mul_f32_e32 v42, v85, v42
	v_mul_f32_e32 v43, v86, v43
	s_waitcnt lgkmcnt(0)
	v_mul_f32_e32 v44, v87, v44
	v_cndmask_b32_e64 v37, v37, -v37, s[10:11]
	v_cndmask_b32_e64 v38, v38, -v38, s[10:11]
	v_cndmask_b32_e64 v39, v39, -v39, s[10:11]
	v_cndmask_b32_e64 v40, v40, -v40, s[10:11]
	v_cndmask_b32_e64 v41, v41, -v41, s[10:11]
	v_cndmask_b32_e64 v42, v42, -v42, s[10:11]
	v_cndmask_b32_e64 v43, v43, -v43, s[10:11]
	v_cndmask_b32_e64 v44, v44, -v44, s[10:11]
	v_addc_co_u32_e32 v63, vcc, 0, v63, vcc
	v_fmac_f32_e32 v37, v88, v29
	v_fmac_f32_e32 v38, v89, v30
	v_fmac_f32_e32 v39, v90, v31
	v_fmac_f32_e32 v40, v91, v32
	v_fmac_f32_e32 v41, v92, v33
	v_fmac_f32_e32 v42, v93, v34
	v_fmac_f32_e32 v43, v94, v35
	v_fmac_f32_e32 v44, v95, v36
	v_cvt_pk_bf16_f32 v30, v37, v38
	v_cvt_pk_bf16_f32 v31, v39, v40
	v_cvt_pk_bf16_f32 v32, v41, v42
	v_cvt_pk_bf16_f32 v33, v43, v44
	global_store_dwordx4 v[62:63], v[30:33], off offset:3328

.LBB0_169:
	s_andn2_saveexec_b64 s[62:63], s[62:63]
	s_cbranch_execz .LBB0_171
	s_waitcnt lgkmcnt(5)
	s_waitcnt lgkmcnt(2)
	s_waitcnt lgkmcnt(1)
	v_add_f32_e32 v37, v45, v46
	v_fmamk_f32 v37, v37, 0x3c000000, v26
	v_mul_f32_e32 v42, 0x4b800000, v37
	v_cmp_gt_f32_e32 vcc, s18, v37
	s_nop 1
	v_cndmask_b32_e32 v37, v37, v42, vcc
	v_rsq_f32_e32 v37, v37
	v_lshlrev_b64 v[42:43], 8, v[0:1]
	s_waitcnt lgkmcnt(0)
	v_mul_f32_e32 v44, 0x45800000, v37
	v_cndmask_b32_e32 v37, v37, v44, vcc
	v_mul_f32_e32 v31, v37, v31
	v_mul_f32_e32 v32, v37, v32
	v_mul_f32_e32 v33, v37, v33
	v_mul_f32_e32 v34, v37, v34
	v_mul_f32_e32 v35, v37, v35
	v_mul_f32_e32 v30, v37, v30
	v_mul_f32_e32 v36, v37, v36
	v_mul_f32_e32 v29, v37, v29
	v_mul_f32_e32 v31, v31, v72
	v_mul_f32_e32 v32, v32, v73
	v_mul_f32_e32 v33, v33, v74
	v_mul_f32_e32 v34, v34, v75
	v_mul_f32_e32 v35, v35, v76
	v_mul_f32_e32 v30, v30, v71
	v_mul_f32_e32 v36, v36, v77
	v_cvt_pk_bf16_f32 v31, v31, v32
	v_cvt_pk_bf16_f32 v32, v33, v34
	v_cvt_pk_bf16_f32 v33, v35, v36
	v_lshl_add_u64 v[34:35], v[8:9], 0, v[42:43]
	v_mul_f32_e32 v29, v29, v70
	v_cvt_pk_bf16_f32 v30, v29, v30
	global_store_dwordx4 v[34:35], v[30:33], off

.LBB0_172:
	s_andn2_saveexec_b64 s[60:61], s[60:61]
	s_cbranch_execz .LBB0_163
	s_waitcnt lgkmcnt(5)
	s_waitcnt lgkmcnt(0)
	v_add_f32_e32 v37, v47, v48
	v_fmamk_f32 v37, v37, 0x3b800000, v26
	v_mul_f32_e32 v46, 0x4b800000, v37
	v_cmp_gt_f32_e32 vcc, s18, v37
	s_nop 1
	v_cndmask_b32_e32 v37, v37, v46, vcc
	v_rsq_f32_e32 v37, v37
	v_lshlrev_b64 v[46:47], 9, v[0:1]
	v_mul_f32_e32 v1, 0x45800000, v37
	v_cndmask_b32_e32 v1, v37, v1, vcc
	v_mul_f32_e32 v31, v1, v31
	v_mul_f32_e32 v32, v1, v32
	v_mul_f32_e32 v33, v1, v33
	v_mul_f32_e32 v34, v1, v34
	v_mul_f32_e32 v35, v1, v35
	v_mul_f32_e32 v29, v1, v29
	v_mul_f32_e32 v30, v1, v30
	v_mul_f32_e32 v1, v1, v36
	v_mul_f32_e32 v31, v31, v72
	v_mul_f32_e32 v32, v32, v73
	v_mul_f32_e32 v33, v33, v74
	v_mul_f32_e32 v34, v34, v75
	v_mul_f32_e32 v35, v35, v76
	v_mul_f32_e32 v30, v30, v71
	v_mul_f32_e32 v1, v1, v77
	v_cvt_pk_bf16_f32 v31, v31, v32
	v_cvt_pk_bf16_f32 v32, v33, v34
	v_cvt_pk_bf16_f32 v33, v35, v1
	v_lshl_add_u64 v[34:35], v[12:13], 0, v[46:47]
	v_mul_f32_e32 v29, v29, v70
	v_cvt_pk_bf16_f32 v30, v29, v30
	global_store_dwordx4 v[34:35], v[30:33], off
	s_branch .LBB0_163
.LBB0_174:
	s_or_b64 exec, exec, s[52:53]
	s_waitcnt vmcnt(0)
	s_mov_b32 s100, 0

.LBB0_540:
	s_cmp_gt_i32 s34, 12
	s_cselect_b64 s[0:1], -1, 0
	s_cmp_lt_i32 s35, 13
	s_cselect_b64 s[2:3], -1, 0
	s_or_b64 s[0:1], s[0:1], s[2:3]
	s_and_b64 vcc, exec, s[0:1]
	s_cbranch_vccnz .LBB0_599
	s_waitcnt vmcnt(0)
	v_mbcnt_lo_u32_b32 v14, -1, 0
	v_mbcnt_hi_u32_b32 v14, -1, v14
	s_mov_b32 s0, 0xc000
	v_add_u32_e32 v16, s84, v14
	v_ashrrev_i32_e32 v18, 6, v16
	v_lshl_add_u32 v0, s12, 3, v18
	v_cmp_gt_i32_e32 vcc, s0, v0
	v_and_b32_e32 v15, 63, v14
	v_lshlrev_b32_e32 v17, 3, v14
	s_and_saveexec_b64 s[20:21], vcc
	s_cbranch_execz .LBB0_554
	v_mbcnt_lo_u32_b32 v1, -1, 0
	v_mbcnt_hi_u32_b32 v1, -1, v1
	v_and_b32_e32 v6, 64, v1
	v_add_u32_e32 v6, 64, v6
	v_xor_b32_e32 v7, 32, v1
	v_cmp_lt_i32_e32 vcc, v7, v6
	v_lshlrev_b32_e32 v10, 4, v15
	v_mov_b32_e32 v11, 0
	v_cndmask_b32_e32 v7, v1, v7, vcc
	v_lshlrev_b32_e32 v19, 2, v7
	v_xor_b32_e32 v7, 16, v1
	v_cmp_lt_i32_e32 vcc, v7, v6
	s_add_u32 s26, s70, 0x16a0000
	v_lshl_add_u64 v[2:3], s[70:71], 0, v[10:11]
	v_cndmask_b32_e32 v7, v1, v7, vcc
	v_lshlrev_b32_e32 v20, 2, v7
	v_xor_b32_e32 v7, 8, v1
	v_cmp_lt_i32_e32 vcc, v7, v6
	s_addc_u32 s27, s71, 0
	s_mov_b64 s[16:17], 0x1dfa0000
	v_cndmask_b32_e32 v7, v1, v7, vcc
	v_lshlrev_b32_e32 v21, 2, v7
	v_xor_b32_e32 v7, 4, v1
	v_cmp_lt_i32_e32 vcc, v7, v6
	s_add_u32 s28, s70, 0x1720000
	s_mov_b64 s[0:1], 0x107a0000
	v_cndmask_b32_e32 v7, v1, v7, vcc
	v_lshlrev_b32_e32 v22, 2, v7
	v_xor_b32_e32 v7, 2, v1
	v_cmp_lt_i32_e32 vcc, v7, v6
	s_addc_u32 s29, s71, 0
	v_lshl_add_u64 v[4:5], v[2:3], 0, s[0:1]
	v_cndmask_b32_e32 v7, v1, v7, vcc
	v_lshlrev_b32_e32 v23, 2, v7
	v_xor_b32_e32 v7, 1, v1
	v_cmp_lt_i32_e32 vcc, v7, v6
	v_mov_b32_e32 v6, 0xffffff00
	v_lshl_add_u32 v10, v15, 3, v6
	v_cndmask_b32_e32 v1, v1, v7, vcc
	v_lshlrev_b32_e32 v24, 2, v1
	v_and_b32_e32 v1, 48, v14
	v_lshl_add_u64 v[8:9], v[10:11], 1, s[70:71]
	v_cmp_eq_u32_e64 s[6:7], 32, v1
	v_and_b32_e32 v1, 8, v17
	v_lshl_add_u64 v[6:7], v[10:11], 2, s[48:49]
	v_lshl_add_u64 v[8:9], v[8:9], 0, s[16:17]
	v_lshlrev_b32_e32 v10, 5, v15
	s_mov_b64 s[16:17], 0x1c7a0000
	v_cmp_gt_u32_e64 s[0:1], 32, v15
	v_cmp_lt_u32_e64 s[2:3], 31, v15
	v_cmp_lt_u32_e64 s[4:5], 47, v15
	v_cmp_gt_u32_e64 s[8:9], 52, v15
	v_cmp_gt_u32_e64 s[10:11], 50, v15
	v_lshl_add_u64 v[10:11], s[44:45], 0, v[10:11]
	v_lshl_add_u64 v[12:13], v[2:3], 0, s[16:17]
	s_waitcnt lgkmcnt(0)
	s_lshl_b32 s16, s13, 3
	s_mov_b64 s[36:37], 0
	s_mov_b32 s17, 0x8000
	v_lshlrev_b32_e32 v25, 2, v1
	v_mov_b32_e32 v26, 0x358637bd
	s_mov_b32 s18, 0x800000
	s_mov_b32 s19, 0xbfff
	v_mov_b32_e32 v27, 0x7ff
	v_mov_b32_e32 v28, 0x1fff
	s_mov_b64 s[22:23], exec
	s_and_b64 exec, s[22:23], s[0:1]
	global_load_dwordx4 v[70:73], v[10:11], off offset:1024
	global_load_dwordx4 v[74:77], v[10:11], off offset:1040
	s_and_b64 exec, s[22:23], s[6:7]
	global_load_dwordx4 v[70:73], v[6:7], off offset:512
	global_load_dwordx4 v[74:77], v[6:7], off offset:528
	s_mov_b64 exec, s[22:23]
	s_mov_b32 s30, 0
	s_lshl_b32 s31, s16, 2
	v_mov_b32_e32 v97, v0
	v_min_i32_e32 v98, s19, v97
	v_cmp_gt_i32_e32 vcc, s17, v98
	v_ashrrev_i32_e32 v99, 31, v98
	v_lshlrev_b64 v[68:69], 10, v[98:99]
	v_lshl_add_u64 v[68:69], v[4:5], 0, v[68:69]
	v_cndmask_b32_e32 v96, v27, v28, vcc
	v_and_b32_e32 v96, v96, v98
	v_lshl_or_b32 v96, v96, 6, v25
	global_load_dwordx4 v[120:123], v96, s[28:29]
	global_load_dwordx4 v[124:127], v96, s[28:29] offset:16
	global_load_dwordx4 v[128:131], v96, s[26:27]
	global_load_dwordx4 v[132:135], v96, s[26:27] offset:16
	global_load_dwordx4 v[100:103], v[68:69], off
	v_add_u32_e32 v97, s16, v97
	v_min_i32_e32 v98, s19, v97
	v_cmp_gt_i32_e32 vcc, s17, v98
	v_ashrrev_i32_e32 v99, 31, v98
	v_lshlrev_b64 v[68:69], 10, v[98:99]
	v_lshl_add_u64 v[68:69], v[4:5], 0, v[68:69]
	v_cndmask_b32_e32 v96, v27, v28, vcc
	v_and_b32_e32 v96, v96, v98
	v_lshl_or_b32 v96, v96, 6, v25
	global_load_dwordx4 v[136:139], v96, s[28:29]
	global_load_dwordx4 v[140:143], v96, s[28:29] offset:16
	global_load_dwordx4 v[144:147], v96, s[26:27]
	global_load_dwordx4 v[148:151], v96, s[26:27] offset:16
	global_load_dwordx4 v[104:107], v[68:69], off
	v_add_u32_e32 v97, s16, v97
	v_min_i32_e32 v98, s19, v97
	v_cmp_gt_i32_e32 vcc, s17, v98
	v_ashrrev_i32_e32 v99, 31, v98
	v_lshlrev_b64 v[68:69], 10, v[98:99]
	v_lshl_add_u64 v[68:69], v[4:5], 0, v[68:69]
	v_cndmask_b32_e32 v96, v27, v28, vcc
	v_and_b32_e32 v96, v96, v98
	v_lshl_or_b32 v96, v96, 6, v25
	global_load_dwordx4 v[152:155], v96, s[28:29]
	global_load_dwordx4 v[156:159], v96, s[28:29] offset:16
	global_load_dwordx4 v[160:163], v96, s[26:27]
	global_load_dwordx4 v[164:167], v96, s[26:27] offset:16
	global_load_dwordx4 v[108:111], v[68:69], off
	v_add_u32_e32 v97, s16, v97
	v_min_i32_e32 v98, s19, v97
	v_cmp_gt_i32_e32 vcc, s17, v98
	v_ashrrev_i32_e32 v99, 31, v98
	v_lshlrev_b64 v[68:69], 10, v[98:99]
	v_lshl_add_u64 v[68:69], v[4:5], 0, v[68:69]
	v_cndmask_b32_e32 v96, v27, v28, vcc
	v_and_b32_e32 v96, v96, v98
	v_lshl_or_b32 v96, v96, 6, v25
	global_load_dwordx4 v[168:171], v96, s[28:29]
	global_load_dwordx4 v[172:175], v96, s[28:29] offset:16
	global_load_dwordx4 v[176:179], v96, s[26:27]
	global_load_dwordx4 v[180:183], v96, s[26:27] offset:16
	global_load_dwordx4 v[112:115], v[68:69], off
	v_add_u32_e32 v97, s16, v97
	s_branch .LBB0_544

.LBB0_544:
	v_ashrrev_i32_e32 v1, 31, v0
	v_add_u32_e32 v98, s31, v0
	v_min_i32_e32 v98, s19, v98
	v_cmp_gt_i32_e32 vcc, s17, v98
	v_ashrrev_i32_e32 v99, 31, v98
	v_lshlrev_b64 v[68:69], 10, v[98:99]
	v_lshl_add_u64 v[68:69], v[4:5], 0, v[68:69]
	v_cndmask_b32_e32 v96, v27, v28, vcc
	v_and_b32_e32 v96, v96, v98
	v_lshl_or_b32 v96, v96, 6, v25
	s_and_b32 s32, s30, 3
	s_add_i32 s30, s30, 1
	s_waitcnt vmcnt(15)
	s_cmp_eq_u32 s32, 0
	s_cbranch_scc1 .Llat544_s0
	s_cmp_eq_u32 s32, 1
	s_cbranch_scc1 .Llat544_s1
	s_cmp_eq_u32 s32, 2
	s_cbranch_scc1 .Llat544_s2
	v_mov_b32_e32 v34, v112
	v_mov_b32_e32 v35, v113
	v_mov_b32_e32 v36, v114
	v_mov_b32_e32 v37, v115
	v_mov_b32_e32 v80, v168
	v_mov_b32_e32 v81, v169
	v_mov_b32_e32 v82, v170
	v_mov_b32_e32 v83, v171
	v_mov_b32_e32 v84, v172
	v_mov_b32_e32 v85, v173
	v_mov_b32_e32 v86, v174
	v_mov_b32_e32 v87, v175
	v_mov_b32_e32 v88, v176
	v_mov_b32_e32 v89, v177
	v_mov_b32_e32 v90, v178
	v_mov_b32_e32 v91, v179
	v_mov_b32_e32 v92, v180
	v_mov_b32_e32 v93, v181
	v_mov_b32_e32 v94, v182
	v_mov_b32_e32 v95, v183
	global_load_dwordx4 v[168:171], v96, s[28:29]
	global_load_dwordx4 v[172:175], v96, s[28:29] offset:16
	global_load_dwordx4 v[176:179], v96, s[26:27]
	global_load_dwordx4 v[180:183], v96, s[26:27] offset:16
	global_load_dwordx4 v[112:115], v[68:69], off
	s_branch .Llat544_body
.Llat544_s0:
	v_mov_b32_e32 v34, v100
	v_mov_b32_e32 v35, v101
	v_mov_b32_e32 v36, v102
	v_mov_b32_e32 v37, v103
	v_mov_b32_e32 v80, v120
	v_mov_b32_e32 v81, v121
	v_mov_b32_e32 v82, v122
	v_mov_b32_e32 v83, v123
	v_mov_b32_e32 v84, v124
	v_mov_b32_e32 v85, v125
	v_mov_b32_e32 v86, v126
	v_mov_b32_e32 v87, v127
	v_mov_b32_e32 v88, v128
	v_mov_b32_e32 v89, v129
	v_mov_b32_e32 v90, v130
	v_mov_b32_e32 v91, v131
	v_mov_b32_e32 v92, v132
	v_mov_b32_e32 v93, v133
	v_mov_b32_e32 v94, v134
	v_mov_b32_e32 v95, v135
	global_load_dwordx4 v[120:123], v96, s[28:29]
	global_load_dwordx4 v[124:127], v96, s[28:29] offset:16
	global_load_dwordx4 v[128:131], v96, s[26:27]
	global_load_dwordx4 v[132:135], v96, s[26:27] offset:16
	global_load_dwordx4 v[100:103], v[68:69], off
	s_branch .Llat544_body
.Llat544_s1:
	v_mov_b32_e32 v34, v104
	v_mov_b32_e32 v35, v105
	v_mov_b32_e32 v36, v106
	v_mov_b32_e32 v37, v107
	v_mov_b32_e32 v80, v136
	v_mov_b32_e32 v81, v137
	v_mov_b32_e32 v82, v138
	v_mov_b32_e32 v83, v139
	v_mov_b32_e32 v84, v140
	v_mov_b32_e32 v85, v141
	v_mov_b32_e32 v86, v142
	v_mov_b32_e32 v87, v143
	v_mov_b32_e32 v88, v144
	v_mov_b32_e32 v89, v145
	v_mov_b32_e32 v90, v146
	v_mov_b32_e32 v91, v147
	v_mov_b32_e32 v92, v148
	v_mov_b32_e32 v93, v149
	v_mov_b32_e32 v94, v150
	v_mov_b32_e32 v95, v151
	global_load_dwordx4 v[136:139], v96, s[28:29]
	global_load_dwordx4 v[140:143], v96, s[28:29] offset:16
	global_load_dwordx4 v[144:147], v96, s[26:27]
	global_load_dwordx4 v[148:151], v96, s[26:27] offset:16
	global_load_dwordx4 v[104:107], v[68:69], off
	s_branch .Llat544_body
.Llat544_s2:
	v_mov_b32_e32 v34, v108
	v_mov_b32_e32 v35, v109
	v_mov_b32_e32 v36, v110
	v_mov_b32_e32 v37, v111
	v_mov_b32_e32 v80, v152
	v_mov_b32_e32 v81, v153
	v_mov_b32_e32 v82, v154
	v_mov_b32_e32 v83, v155
	v_mov_b32_e32 v84, v156
	v_mov_b32_e32 v85, v157
	v_mov_b32_e32 v86, v158
	v_mov_b32_e32 v87, v159
	v_mov_b32_e32 v88, v160
	v_mov_b32_e32 v89, v161
	v_mov_b32_e32 v90, v162
	v_mov_b32_e32 v91, v163
	v_mov_b32_e32 v92, v164
	v_mov_b32_e32 v93, v165
	v_mov_b32_e32 v94, v166
	v_mov_b32_e32 v95, v167
	global_load_dwordx4 v[152:155], v96, s[28:29]
	global_load_dwordx4 v[156:159], v96, s[28:29] offset:16
	global_load_dwordx4 v[160:163], v96, s[26:27]
	global_load_dwordx4 v[164:167], v96, s[26:27] offset:16
	global_load_dwordx4 v[108:111], v[68:69], off
.Llat544_body:
	v_and_b32_e32 v30, 0xffff0000, v34
	v_lshlrev_b32_e32 v29, 16, v34
	v_lshlrev_b32_e32 v31, 16, v35
	v_and_b32_e32 v32, 0xffff0000, v35
	v_lshlrev_b32_e32 v33, 16, v36
	v_and_b32_e32 v34, 0xffff0000, v36
	v_lshlrev_b32_e32 v35, 16, v37
	v_and_b32_e32 v36, 0xffff0000, v37
	v_mul_f32_e32 v37, v30, v30
	v_fmac_f32_e32 v37, v29, v29
	v_fmac_f32_e32 v37, v31, v31
	v_fmac_f32_e32 v37, v32, v32
	v_fmac_f32_e32 v37, v33, v33
	v_fmac_f32_e32 v37, v34, v34
	v_fmac_f32_e32 v37, v35, v35
	v_fmac_f32_e32 v37, v36, v36
	v_cndmask_b32_e64 v38, 0, v37, s[0:1]
	v_cndmask_b32_e64 v37, 0, v37, s[6:7]
	ds_bpermute_b32 v39, v19, v38
	ds_bpermute_b32 v40, v19, v37
	s_waitcnt lgkmcnt(1)
	v_add_f32_e32 v38, v38, v39
	s_waitcnt lgkmcnt(0)
	v_add_f32_e32 v37, v37, v40
	ds_bpermute_b32 v39, v20, v38
	ds_bpermute_b32 v40, v20, v37
	s_waitcnt lgkmcnt(1)
	v_add_f32_e32 v38, v38, v39
	s_waitcnt lgkmcnt(0)
	v_add_f32_e32 v39, v37, v40
	ds_bpermute_b32 v40, v21, v38
	ds_bpermute_b32 v41, v21, v39
	ds_bpermute_b32 v37, v23, v29
	s_waitcnt lgkmcnt(2)
	v_add_f32_e32 v42, v38, v40
	s_waitcnt lgkmcnt(1)
	v_add_f32_e32 v41, v39, v41
	ds_bpermute_b32 v43, v22, v42
	ds_bpermute_b32 v44, v22, v41
	ds_bpermute_b32 v38, v23, v30
	ds_bpermute_b32 v39, v23, v31
	ds_bpermute_b32 v40, v23, v32
	s_waitcnt lgkmcnt(4)
	v_add_f32_e32 v45, v42, v43
	s_waitcnt lgkmcnt(3)
	v_add_f32_e32 v44, v41, v44
	ds_bpermute_b32 v46, v23, v45
	ds_bpermute_b32 v48, v23, v44
	ds_bpermute_b32 v41, v23, v33
	ds_bpermute_b32 v42, v23, v34
	ds_bpermute_b32 v43, v23, v35
	s_waitcnt lgkmcnt(4)
	v_add_f32_e32 v47, v45, v46
	s_waitcnt lgkmcnt(3)
	v_add_f32_e32 v45, v44, v48
	ds_bpermute_b32 v48, v24, v47
	ds_bpermute_b32 v46, v24, v45
	ds_bpermute_b32 v44, v23, v36
	s_and_saveexec_b64 s[22:23], s[2:3]
	s_xor_b64 s[38:39], exec, s[22:23]
	s_cbranch_execz .LBB0_552
	s_and_saveexec_b64 s[22:23], s[4:5]
	s_xor_b64 s[40:41], exec, s[22:23]
	s_cbranch_execz .LBB0_549
	s_and_saveexec_b64 s[42:43], s[8:9]
	s_cbranch_execz .LBB0_548
	v_lshlrev_b64 v[62:63], 6, v[0:1]
	v_lshl_add_u64 v[62:63], v[2:3], 0, v[62:63]
	s_waitcnt lgkmcnt(1)
	v_add_co_u32_e32 v62, vcc, 0x1eb9f000, v62
	v_mul_f32_e32 v37, v80, v37
	v_mul_f32_e32 v38, v81, v38
	v_mul_f32_e32 v39, v82, v39
	v_mul_f32_e32 v40, v83, v40
	v_mul_f32_e32 v41, v84, v41
	v_mul_f32_e32 v42, v85, v42
	v_mul_f32_e32 v43, v86, v43
	s_waitcnt lgkmcnt(0)
	v_mul_f32_e32 v44, v87, v44
	v_cndmask_b32_e64 v37, v37, -v37, s[10:11]
	v_cndmask_b32_e64 v38, v38, -v38, s[10:11]
	v_cndmask_b32_e64 v39, v39, -v39, s[10:11]
	v_cndmask_b32_e64 v40, v40, -v40, s[10:11]
	v_cndmask_b32_e64 v41, v41, -v41, s[10:11]
	v_cndmask_b32_e64 v42, v42, -v42, s[10:11]
	v_cndmask_b32_e64 v43, v43, -v43, s[10:11]
	v_cndmask_b32_e64 v44, v44, -v44, s[10:11]
	v_addc_co_u32_e32 v63, vcc, 0, v63, vcc
	v_fmac_f32_e32 v37, v88, v29
	v_fmac_f32_e32 v38, v89, v30
	v_fmac_f32_e32 v39, v90, v31
	v_fmac_f32_e32 v40, v91, v32
	v_fmac_f32_e32 v41, v92, v33
	v_fmac_f32_e32 v42, v93, v34
	v_fmac_f32_e32 v43, v94, v35
	v_fmac_f32_e32 v44, v95, v36
	v_cvt_pk_bf16_f32 v30, v37, v38
	v_cvt_pk_bf16_f32 v31, v39, v40
	v_cvt_pk_bf16_f32 v32, v41, v42
	v_cvt_pk_bf16_f32 v33, v43, v44
	global_store_dwordx4 v[62:63], v[30:33], off offset:3328

.LBB0_549:
	s_andn2_saveexec_b64 s[40:41], s[40:41]
	s_cbranch_execz .LBB0_551
	s_waitcnt lgkmcnt(5)
	s_waitcnt lgkmcnt(2)
	s_waitcnt lgkmcnt(1)
	v_add_f32_e32 v37, v45, v46
	v_fmamk_f32 v37, v37, 0x3c000000, v26
	v_mul_f32_e32 v42, 0x4b800000, v37
	v_cmp_gt_f32_e32 vcc, s18, v37
	s_nop 1
	v_cndmask_b32_e32 v37, v37, v42, vcc
	v_rsq_f32_e32 v37, v37
	v_lshlrev_b64 v[42:43], 8, v[0:1]
	s_waitcnt lgkmcnt(0)
	v_mul_f32_e32 v44, 0x45800000, v37
	v_cndmask_b32_e32 v37, v37, v44, vcc
	v_mul_f32_e32 v31, v37, v31
	v_mul_f32_e32 v32, v37, v32
	v_mul_f32_e32 v33, v37, v33
	v_mul_f32_e32 v34, v37, v34
	v_mul_f32_e32 v35, v37, v35
	v_mul_f32_e32 v30, v37, v30
	v_mul_f32_e32 v36, v37, v36
	v_mul_f32_e32 v29, v37, v29
	v_mul_f32_e32 v31, v31, v72
	v_mul_f32_e32 v32, v32, v73
	v_mul_f32_e32 v33, v33, v74
	v_mul_f32_e32 v34, v34, v75
	v_mul_f32_e32 v35, v35, v76
	v_mul_f32_e32 v30, v30, v71
	v_mul_f32_e32 v36, v36, v77
	v_cvt_pk_bf16_f32 v31, v31, v32
	v_cvt_pk_bf16_f32 v32, v33, v34
	v_cvt_pk_bf16_f32 v33, v35, v36
	v_lshl_add_u64 v[34:35], v[8:9], 0, v[42:43]
	v_mul_f32_e32 v29, v29, v70
	v_cvt_pk_bf16_f32 v30, v29, v30
	global_store_dwordx4 v[34:35], v[30:33], off

.LBB0_552:
	s_andn2_saveexec_b64 s[38:39], s[38:39]
	s_cbranch_execz .LBB0_543
	s_waitcnt lgkmcnt(5)
	s_waitcnt lgkmcnt(0)
	v_add_f32_e32 v37, v47, v48
	v_fmamk_f32 v37, v37, 0x3b800000, v26
	v_mul_f32_e32 v46, 0x4b800000, v37
	v_cmp_gt_f32_e32 vcc, s18, v37
	s_nop 1
	v_cndmask_b32_e32 v37, v37, v46, vcc
	v_rsq_f32_e32 v37, v37
	v_lshlrev_b64 v[46:47], 9, v[0:1]
	v_mul_f32_e32 v1, 0x45800000, v37
	v_cndmask_b32_e32 v1, v37, v1, vcc
	v_mul_f32_e32 v31, v1, v31
	v_mul_f32_e32 v32, v1, v32
	v_mul_f32_e32 v33, v1, v33
	v_mul_f32_e32 v34, v1, v34
	v_mul_f32_e32 v35, v1, v35
	v_mul_f32_e32 v29, v1, v29
	v_mul_f32_e32 v30, v1, v30
	v_mul_f32_e32 v1, v1, v36
	v_mul_f32_e32 v31, v31, v72
	v_mul_f32_e32 v32, v32, v73
	v_mul_f32_e32 v33, v33, v74
	v_mul_f32_e32 v34, v34, v75
	v_mul_f32_e32 v35, v35, v76
	v_mul_f32_e32 v30, v30, v71
	v_mul_f32_e32 v1, v1, v77
	v_cvt_pk_bf16_f32 v31, v31, v32
	v_cvt_pk_bf16_f32 v32, v33, v34
	v_cvt_pk_bf16_f32 v33, v35, v1
	v_lshl_add_u64 v[34:35], v[12:13], 0, v[46:47]
	v_mul_f32_e32 v29, v29, v70
	v_cvt_pk_bf16_f32 v30, v29, v30
	global_store_dwordx4 v[34:35], v[30:33], off
	s_branch .LBB0_543
.LBB0_554:
	s_or_b64 exec, exec, s[20:21]
	s_waitcnt vmcnt(0)
	s_mov_b32 s100, 1
	s_branch .Ldil_body
